# rglru scan loop: next-step bf16 loads land in free VGPRs and are unpacked at the loop bottom / exit instead of being waited on right after issue
# baseline (speedup 1.0000x reference)
.LBB0_611:
	v_add_u32_e32 v22, 16, v44
	v_ashrrev_i32_e32 v23, 31, v22
	v_add_u32_e32 v64, 17, v44
	v_lshlrev_b64 v[22:23], 10, v[22:23]
	v_ashrrev_i32_e32 v65, 31, v64
	v_lshl_add_u64 v[22:23], v[32:33], 0, v[22:23]
	v_lshl_add_u64 v[24:25], s[38:39], 0, v[34:35]
	v_lshlrev_b64 v[64:65], 10, v[64:65]
	v_lshl_add_u64 v[64:65], v[32:33], 0, v[64:65]
	global_load_dword v52, v[22:23], off
	global_load_dword v51, v[64:65], off
	v_add_co_u32_e32 v22, vcc, 0x9ab6000, v24
	v_add_u32_e32 v64, 18, v44
	s_nop 0
	v_addc_co_u32_e32 v23, vcc, 0, v25, vcc
	v_add_u32_e32 v66, 19, v44
	v_ashrrev_i32_e32 v65, 31, v64
	v_ashrrev_i32_e32 v67, 31, v66
	global_load_ushort v130, v[22:23], off offset:512
	global_load_ushort v131, v[22:23], off offset:2048
	global_load_ushort v132, v[22:23], off offset:3584
	v_add_co_u32_e32 v22, vcc, 0x9ab7000, v24
	v_lshlrev_b64 v[64:65], 10, v[64:65]
	v_lshlrev_b64 v[66:67], 10, v[66:67]
	v_addc_co_u32_e32 v23, vcc, 0, v25, vcc
	v_lshl_add_u64 v[64:65], v[32:33], 0, v[64:65]
	v_lshl_add_u64 v[66:67], v[32:33], 0, v[66:67]
	global_load_ushort v133, v[22:23], off offset:1024
	s_nop 0
	global_load_dword v43, v[64:65], off
	global_load_dword v17, v[66:67], off

.LBB0_616:
	s_mov_b64 s[10:11], 0x6000
	s_add_i32 s16, s16, 16
	v_lshl_add_u64 v[34:35], v[34:35], 0, s[10:11]
	s_mov_b64 s[10:11], 0x8000
	v_add_u32_e32 v60, 0x2100, v60
	v_lshl_add_u64 v[36:37], v[36:37], 0, s[66:67]
	v_lshl_add_u64 v[38:39], v[38:39], 0, s[66:67]
	v_lshl_add_u64 v[40:41], v[40:41], 0, s[10:11]
	s_cmpk_eq_i32 s16, 0x70
	v_add_u32_e32 v62, 0x2100, v62
	s_cbranch_scc1 .LBB0_618
	s_waitcnt vmcnt(0)
	v_mov_b32_e32 v42, v52
	v_mov_b32_e32 v58, v51
	s_waitcnt vmcnt(1)
	v_mov_b32_e32 v57, v43
	s_waitcnt vmcnt(0)
	v_mov_b32_e32 v55, v17
	v_mov_b32_e32 v54, v64
	v_mov_b32_e32 v63, v45
	s_and_b64 s[98:99], exec, s[26:27]
	s_cbranch_scc1 .Lrg_nu1
	v_lshlrev_b32_e32 v24, 16, v130
	v_lshlrev_b32_e32 v25, 16, v131
	v_lshlrev_b32_e32 v23, 16, v133
	v_lshlrev_b32_e32 v22, 16, v132
.Lrg_nu1:
	v_mov_b64_e32 v[30:31], v[24:25]
	v_mov_b64_e32 v[28:29], v[22:23]
	s_and_b64 vcc, exec, s[26:27]
	v_add_u32_e32 v44, s16, v61
	v_mov_b32_e32 v52, v42
	s_cbranch_vccz .LBB0_611
	s_branch .LBB0_612
.LBB0_618:
	s_and_b64 s[98:99], exec, s[26:27]
	s_cbranch_scc1 .Lrg_nu2
	s_waitcnt vmcnt(2)
	v_lshlrev_b32_e32 v24, 16, v130
	v_lshlrev_b32_e32 v25, 16, v131
	v_lshlrev_b32_e32 v23, 16, v133
	v_lshlrev_b32_e32 v22, 16, v132
